# FFN-out fused epilogue: final-norm gain loads issued with the residual loads ahead of the row-statistics exchange and kept in registers for pass 2
# speedup vs baseline: 1.0057x; 1.0057x over previous
.LBB0_702:
	s_andn2_b64 vcc, exec, s[50:51]
	s_cbranch_vccnz .LBB0_740
	v_lshlrev_b32_e32 v250, 2, v182
	v_mov_b32_e32 v251, 0
	v_lshl_add_u64 v[250:251], v[250:251], 0, s[76:77]
	global_load_dwordx4 v[234:237], v[250:251], off
	global_load_dwordx4 v[238:241], v[250:251], off offset:16
	global_load_dwordx4 v[242:245], v[250:251], off offset:512
	global_load_dwordx4 v[246:249], v[250:251], off offset:528
	v_lshlrev_b32_e32 v130, 1, v182
	v_lshl_add_u32 v170, v180, 11, v130
	v_or_b32_e32 v188, 0x100, v170
	global_load_dwordx4 v[190:193], v170, s[40:41]
	global_load_dwordx4 v[194:197], v188, s[40:41]
	v_add_u32_e32 v186, 0x8000, v170
	v_add_u32_e32 v184, 0x8100, v170
	v_add_u32_e32 v160, 0x10000, v170
	v_add_u32_e32 v158, 0x10100, v170
	v_add_u32_e32 v156, 0x18000, v170
	v_add_u32_e32 v154, 0x18100, v170
	global_load_dwordx4 v[150:153], v186, s[40:41]
	global_load_dwordx4 v[146:149], v184, s[40:41]
	global_load_dwordx4 v[142:145], v160, s[40:41]
	global_load_dwordx4 v[138:141], v158, s[40:41]
	global_load_dwordx4 v[134:137], v156, s[40:41]
	global_load_dwordx4 v[130:133], v154, s[40:41]
	v_and_b32_e32 v157, 64, v211
	v_xor_b32_e32 v155, 16, v211
	v_add_u32_e32 v157, 64, v157
	v_cmp_lt_i32_e32 vcc, v155, v157
	s_waitcnt vmcnt(0)
	v_lshlrev_b32_e32 v198, 16, v190
	v_and_b32_e32 v199, 0xffff0000, v190
	v_lshlrev_b32_e32 v190, 16, v191
	v_and_b32_e32 v191, 0xffff0000, v191
	v_lshlrev_b32_e32 v202, 16, v194
	v_and_b32_e32 v203, 0xffff0000, v194
	v_lshlrev_b32_e32 v194, 16, v195
	v_and_b32_e32 v195, 0xffff0000, v195
	v_lshlrev_b32_e32 v200, 16, v192
	v_and_b32_e32 v201, 0xffff0000, v192
	v_pk_add_f32 v[128:129], v[128:129], v[190:191]
	v_pk_add_f32 v[126:127], v[126:127], v[198:199]
	v_lshlrev_b32_e32 v204, 16, v196
	v_and_b32_e32 v205, 0xffff0000, v196
	v_pk_add_f32 v[112:113], v[112:113], v[194:195]
	v_pk_add_f32 v[110:111], v[110:111], v[202:203]
	v_lshlrev_b32_e32 v192, 16, v193
	v_and_b32_e32 v193, 0xffff0000, v193
	v_pk_add_f32 v[122:123], v[122:123], v[200:201]
	v_lshlrev_b32_e32 v196, 16, v197
	v_and_b32_e32 v197, 0xffff0000, v197
	v_mul_f32_e32 v159, v127, v127
	v_mul_f32_e32 v161, v129, v129
	v_pk_add_f32 v[106:107], v[106:107], v[204:205]
	v_mul_f32_e32 v185, v111, v111
	v_mul_f32_e32 v187, v113, v113
	v_pk_add_f32 v[124:125], v[124:125], v[192:193]
	v_mul_f32_e32 v181, v123, v123
	v_pk_add_f32 v[108:109], v[108:109], v[196:197]
	v_fmac_f32_e32 v159, v126, v126
	v_fmac_f32_e32 v161, v128, v128
	v_mul_f32_e32 v189, v107, v107
	v_fmac_f32_e32 v185, v110, v110
	v_fmac_f32_e32 v187, v112, v112
	v_mul_f32_e32 v183, v125, v125
	v_fmac_f32_e32 v181, v122, v122
	v_mul_f32_e32 v190, v109, v109
	v_add_f32_e32 v159, v159, v161
	v_fmac_f32_e32 v189, v106, v106
	v_add_f32_e32 v161, v185, v187
	v_fmac_f32_e32 v183, v124, v124
	v_add_f32_e32 v159, v181, v159
	v_add_f32_e32 v161, v189, v161
	v_fmac_f32_e32 v190, v108, v108
	v_cndmask_b32_e32 v155, v211, v155, vcc
	v_add_f32_e32 v159, v183, v159
	v_add_f32_e32 v161, v190, v161
	v_lshlrev_b32_e32 v155, 2, v155
	v_add_f32_e32 v159, v159, v161
	v_mov_b32_e32 v161, v159
	s_nop 1
	v_permlane16_swap_b32_e32 v161, v159
	s_nop 1
	v_xor_b32_e32 v181, 32, v211
	v_cmp_lt_i32_e32 vcc, v181, v157
	s_waitcnt lgkmcnt(0)
	v_add_f32_e32 v159, v159, v161
	v_cndmask_b32_e32 v157, v211, v181, vcc
	v_lshlrev_b32_e32 v157, 2, v157
	v_mov_b32_e32 v161, v159
	s_nop 1
	v_permlane32_swap_b32_e32 v161, v159
	s_nop 1
	s_and_saveexec_b64 s[50:51], s[4:5]
	s_cbranch_execz .LBB0_705
	s_waitcnt lgkmcnt(0)
	v_add_f32_e32 v159, v159, v161
	ds_write_b32 v218, v159

.LBB0_739:
	s_or_b64 exec, exec, s[48:49]
	s_waitcnt lgkmcnt(0)
	s_barrier
	v_add_u32_e32 v181, 0x1000, v212
	ds_read2_b32 v[150:151], v181 offset1:16
	ds_read2_b32 v[152:153], v181 offset0:32 offset1:48
	ds_read2_b32 v[154:155], v181 offset0:128 offset1:144
	ds_read2_b32 v[156:157], v181 offset0:160 offset1:176
	v_lshlrev_b32_e32 v170, 2, v182
	v_lshl_add_u32 v170, v180, 12, v170
	s_waitcnt vmcnt(0) lgkmcnt(0)
	v_mov_b32_e32 v160, v150
	v_pk_mul_f32 v[126:127], v[126:127], v[160:161] op_sel_hi:[1,0]
	v_pk_mul_f32 v[128:129], v[128:129], v[160:161] op_sel_hi:[1,0]
	v_pk_mul_f32 v[126:127], v[126:127], v[234:235]
	v_pk_mul_f32 v[128:129], v[128:129], v[236:237]
	global_store_dwordx4 v170, v[126:129], s[78:79]
	v_pk_mul_f32 v[122:123], v[122:123], v[160:161] op_sel_hi:[1,0]
	v_pk_mul_f32 v[124:125], v[124:125], v[160:161] op_sel_hi:[1,0]
	v_pk_mul_f32 v[122:123], v[122:123], v[238:239]
	v_pk_mul_f32 v[124:125], v[124:125], v[240:241]
	global_store_dwordx4 v170, v[122:125], s[78:79] offset:16
	v_pk_mul_f32 v[110:111], v[110:111], v[160:161] op_sel_hi:[1,0]
	v_pk_mul_f32 v[112:113], v[112:113], v[160:161] op_sel_hi:[1,0]
	v_pk_mul_f32 v[110:111], v[110:111], v[242:243]
	v_pk_mul_f32 v[112:113], v[112:113], v[244:245]
	global_store_dwordx4 v170, v[110:113], s[78:79] offset:512
	v_pk_mul_f32 v[106:107], v[106:107], v[160:161] op_sel_hi:[1,0]
	v_pk_mul_f32 v[108:109], v[108:109], v[160:161] op_sel_hi:[1,0]
	v_pk_mul_f32 v[106:107], v[106:107], v[246:247]
	v_pk_mul_f32 v[108:109], v[108:109], v[248:249]
	global_store_dwordx4 v170, v[106:109], s[78:79] offset:528
	v_mov_b32_e32 v160, v151
	v_add_u32_e32 v158, 0x10000, v170
	v_pk_mul_f32 v[118:119], v[118:119], v[160:161] op_sel_hi:[1,0]
	v_pk_mul_f32 v[120:121], v[120:121], v[160:161] op_sel_hi:[1,0]
	v_pk_mul_f32 v[118:119], v[118:119], v[234:235]
	v_pk_mul_f32 v[120:121], v[120:121], v[236:237]
	global_store_dwordx4 v158, v[118:121], s[78:79]
	v_pk_mul_f32 v[114:115], v[114:115], v[160:161] op_sel_hi:[1,0]
	v_pk_mul_f32 v[116:117], v[116:117], v[160:161] op_sel_hi:[1,0]
	v_pk_mul_f32 v[114:115], v[114:115], v[238:239]
	v_pk_mul_f32 v[116:117], v[116:117], v[240:241]
	global_store_dwordx4 v158, v[114:117], s[78:79] offset:16
	v_pk_mul_f32 v[94:95], v[94:95], v[160:161] op_sel_hi:[1,0]
	v_pk_mul_f32 v[96:97], v[96:97], v[160:161] op_sel_hi:[1,0]
	v_pk_mul_f32 v[94:95], v[94:95], v[242:243]
	v_pk_mul_f32 v[96:97], v[96:97], v[244:245]
	global_store_dwordx4 v158, v[94:97], s[78:79] offset:512
	v_pk_mul_f32 v[90:91], v[90:91], v[160:161] op_sel_hi:[1,0]
	v_pk_mul_f32 v[92:93], v[92:93], v[160:161] op_sel_hi:[1,0]
	v_pk_mul_f32 v[90:91], v[90:91], v[246:247]
	v_pk_mul_f32 v[92:93], v[92:93], v[248:249]
	global_store_dwordx4 v158, v[90:93], s[78:79] offset:528
	v_mov_b32_e32 v160, v152
	v_add_u32_e32 v158, 0x20000, v170
	v_pk_mul_f32 v[102:103], v[102:103], v[160:161] op_sel_hi:[1,0]
	v_pk_mul_f32 v[104:105], v[104:105], v[160:161] op_sel_hi:[1,0]
	v_pk_mul_f32 v[102:103], v[102:103], v[234:235]
	v_pk_mul_f32 v[104:105], v[104:105], v[236:237]
	global_store_dwordx4 v158, v[102:105], s[78:79]
	v_pk_mul_f32 v[98:99], v[98:99], v[160:161] op_sel_hi:[1,0]
	v_pk_mul_f32 v[100:101], v[100:101], v[160:161] op_sel_hi:[1,0]
	v_pk_mul_f32 v[98:99], v[98:99], v[238:239]
	v_pk_mul_f32 v[100:101], v[100:101], v[240:241]
	global_store_dwordx4 v158, v[98:101], s[78:79] offset:16
	v_pk_mul_f32 v[78:79], v[78:79], v[160:161] op_sel_hi:[1,0]
	v_pk_mul_f32 v[80:81], v[80:81], v[160:161] op_sel_hi:[1,0]
	v_pk_mul_f32 v[78:79], v[78:79], v[242:243]
	v_pk_mul_f32 v[80:81], v[80:81], v[244:245]
	global_store_dwordx4 v158, v[78:81], s[78:79] offset:512
	v_pk_mul_f32 v[74:75], v[74:75], v[160:161] op_sel_hi:[1,0]
	v_pk_mul_f32 v[76:77], v[76:77], v[160:161] op_sel_hi:[1,0]
	v_pk_mul_f32 v[74:75], v[74:75], v[246:247]
	v_pk_mul_f32 v[76:77], v[76:77], v[248:249]
	global_store_dwordx4 v158, v[74:77], s[78:79] offset:528
	v_mov_b32_e32 v160, v153
	v_add_u32_e32 v158, 0x30000, v170
	v_pk_mul_f32 v[86:87], v[86:87], v[160:161] op_sel_hi:[1,0]
	v_pk_mul_f32 v[88:89], v[88:89], v[160:161] op_sel_hi:[1,0]
	v_pk_mul_f32 v[86:87], v[86:87], v[234:235]
	v_pk_mul_f32 v[88:89], v[88:89], v[236:237]
	global_store_dwordx4 v158, v[86:89], s[78:79]
	v_pk_mul_f32 v[82:83], v[82:83], v[160:161] op_sel_hi:[1,0]
	v_pk_mul_f32 v[84:85], v[84:85], v[160:161] op_sel_hi:[1,0]
	v_pk_mul_f32 v[82:83], v[82:83], v[238:239]
	v_pk_mul_f32 v[84:85], v[84:85], v[240:241]
	global_store_dwordx4 v158, v[82:85], s[78:79] offset:16
	v_pk_mul_f32 v[70:71], v[70:71], v[160:161] op_sel_hi:[1,0]
	v_pk_mul_f32 v[72:73], v[72:73], v[160:161] op_sel_hi:[1,0]
	v_pk_mul_f32 v[70:71], v[70:71], v[242:243]
	v_pk_mul_f32 v[72:73], v[72:73], v[244:245]
	global_store_dwordx4 v158, v[70:73], s[78:79] offset:512
	v_pk_mul_f32 v[66:67], v[66:67], v[160:161] op_sel_hi:[1,0]
	v_pk_mul_f32 v[68:69], v[68:69], v[160:161] op_sel_hi:[1,0]
	v_pk_mul_f32 v[66:67], v[66:67], v[246:247]
	v_pk_mul_f32 v[68:69], v[68:69], v[248:249]
	global_store_dwordx4 v158, v[66:69], s[78:79] offset:528
	v_mov_b32_e32 v160, v154
	v_add_u32_e32 v158, 0x80000, v170
	v_pk_mul_f32 v[62:63], v[62:63], v[160:161] op_sel_hi:[1,0]
	v_pk_mul_f32 v[64:65], v[64:65], v[160:161] op_sel_hi:[1,0]
	v_pk_mul_f32 v[62:63], v[62:63], v[234:235]
	v_pk_mul_f32 v[64:65], v[64:65], v[236:237]
	global_store_dwordx4 v158, v[62:65], s[78:79]
	v_pk_mul_f32 v[58:59], v[58:59], v[160:161] op_sel_hi:[1,0]
	v_pk_mul_f32 v[60:61], v[60:61], v[160:161] op_sel_hi:[1,0]
	v_pk_mul_f32 v[58:59], v[58:59], v[238:239]
	v_pk_mul_f32 v[60:61], v[60:61], v[240:241]
	global_store_dwordx4 v158, v[58:61], s[78:79] offset:16
	v_pk_mul_f32 v[46:47], v[46:47], v[160:161] op_sel_hi:[1,0]
	v_pk_mul_f32 v[48:49], v[48:49], v[160:161] op_sel_hi:[1,0]
	v_pk_mul_f32 v[46:47], v[46:47], v[242:243]
	v_pk_mul_f32 v[48:49], v[48:49], v[244:245]
	global_store_dwordx4 v158, v[46:49], s[78:79] offset:512
	v_pk_mul_f32 v[42:43], v[42:43], v[160:161] op_sel_hi:[1,0]
	v_pk_mul_f32 v[44:45], v[44:45], v[160:161] op_sel_hi:[1,0]
	v_pk_mul_f32 v[42:43], v[42:43], v[246:247]
	v_pk_mul_f32 v[44:45], v[44:45], v[248:249]
	global_store_dwordx4 v158, v[42:45], s[78:79] offset:528
	v_mov_b32_e32 v160, v155
	v_add_u32_e32 v158, 0x90000, v170
	v_pk_mul_f32 v[54:55], v[54:55], v[160:161] op_sel_hi:[1,0]
	v_pk_mul_f32 v[56:57], v[56:57], v[160:161] op_sel_hi:[1,0]
	v_pk_mul_f32 v[54:55], v[54:55], v[234:235]
	v_pk_mul_f32 v[56:57], v[56:57], v[236:237]
	global_store_dwordx4 v158, v[54:57], s[78:79]
	v_pk_mul_f32 v[50:51], v[50:51], v[160:161] op_sel_hi:[1,0]
	v_pk_mul_f32 v[52:53], v[52:53], v[160:161] op_sel_hi:[1,0]
	v_pk_mul_f32 v[50:51], v[50:51], v[238:239]
	v_pk_mul_f32 v[52:53], v[52:53], v[240:241]
	global_store_dwordx4 v158, v[50:53], s[78:79] offset:16
	v_pk_mul_f32 v[30:31], v[30:31], v[160:161] op_sel_hi:[1,0]
	v_pk_mul_f32 v[32:33], v[32:33], v[160:161] op_sel_hi:[1,0]
	v_pk_mul_f32 v[30:31], v[30:31], v[242:243]
	v_pk_mul_f32 v[32:33], v[32:33], v[244:245]
	global_store_dwordx4 v158, v[30:33], s[78:79] offset:512
	v_pk_mul_f32 v[26:27], v[26:27], v[160:161] op_sel_hi:[1,0]
	v_pk_mul_f32 v[28:29], v[28:29], v[160:161] op_sel_hi:[1,0]
	v_pk_mul_f32 v[26:27], v[26:27], v[246:247]
	v_pk_mul_f32 v[28:29], v[28:29], v[248:249]
	global_store_dwordx4 v158, v[26:29], s[78:79] offset:528
	v_mov_b32_e32 v160, v156
	v_add_u32_e32 v158, 0xa0000, v170
	v_pk_mul_f32 v[38:39], v[38:39], v[160:161] op_sel_hi:[1,0]
	v_pk_mul_f32 v[40:41], v[40:41], v[160:161] op_sel_hi:[1,0]
	v_pk_mul_f32 v[38:39], v[38:39], v[234:235]
	v_pk_mul_f32 v[40:41], v[40:41], v[236:237]
	global_store_dwordx4 v158, v[38:41], s[78:79]
	v_pk_mul_f32 v[34:35], v[34:35], v[160:161] op_sel_hi:[1,0]
	v_pk_mul_f32 v[36:37], v[36:37], v[160:161] op_sel_hi:[1,0]
	v_pk_mul_f32 v[34:35], v[34:35], v[238:239]
	v_pk_mul_f32 v[36:37], v[36:37], v[240:241]
	global_store_dwordx4 v158, v[34:37], s[78:79] offset:16
	v_pk_mul_f32 v[14:15], v[14:15], v[160:161] op_sel_hi:[1,0]
	v_pk_mul_f32 v[16:17], v[16:17], v[160:161] op_sel_hi:[1,0]
	v_pk_mul_f32 v[14:15], v[14:15], v[242:243]
	v_pk_mul_f32 v[16:17], v[16:17], v[244:245]
	global_store_dwordx4 v158, v[14:17], s[78:79] offset:512
	v_pk_mul_f32 v[10:11], v[10:11], v[160:161] op_sel_hi:[1,0]
	v_pk_mul_f32 v[12:13], v[12:13], v[160:161] op_sel_hi:[1,0]
	v_pk_mul_f32 v[10:11], v[10:11], v[246:247]
	v_pk_mul_f32 v[12:13], v[12:13], v[248:249]
	global_store_dwordx4 v158, v[10:13], s[78:79] offset:528
	v_mov_b32_e32 v160, v157
	v_add_u32_e32 v158, 0xb0000, v170
	v_pk_mul_f32 v[22:23], v[22:23], v[160:161] op_sel_hi:[1,0]
	v_pk_mul_f32 v[24:25], v[24:25], v[160:161] op_sel_hi:[1,0]
	v_pk_mul_f32 v[22:23], v[22:23], v[234:235]
	v_pk_mul_f32 v[24:25], v[24:25], v[236:237]
	global_store_dwordx4 v158, v[22:25], s[78:79]
	v_pk_mul_f32 v[18:19], v[18:19], v[160:161] op_sel_hi:[1,0]
	v_pk_mul_f32 v[20:21], v[20:21], v[160:161] op_sel_hi:[1,0]
	v_pk_mul_f32 v[18:19], v[18:19], v[238:239]
	v_pk_mul_f32 v[20:21], v[20:21], v[240:241]
	global_store_dwordx4 v158, v[18:21], s[78:79] offset:16
	v_pk_mul_f32 v[6:7], v[6:7], v[160:161] op_sel_hi:[1,0]
	v_pk_mul_f32 v[8:9], v[8:9], v[160:161] op_sel_hi:[1,0]
	v_pk_mul_f32 v[6:7], v[6:7], v[242:243]
	v_pk_mul_f32 v[8:9], v[8:9], v[244:245]
	global_store_dwordx4 v158, v[6:9], s[78:79] offset:512
	v_pk_mul_f32 v[2:3], v[2:3], v[160:161] op_sel_hi:[1,0]
	v_pk_mul_f32 v[4:5], v[4:5], v[160:161] op_sel_hi:[1,0]
	v_pk_mul_f32 v[2:3], v[2:3], v[246:247]
	v_pk_mul_f32 v[4:5], v[4:5], v[248:249]
	global_store_dwordx4 v158, v[2:5], s[78:79] offset:528
